# P6 residual epilogue de-serialised: the 32 in-place 8-byte loads hoisted into 2 batches of 16 in flight with counted vmcnt instead of a load-wait-store chain
# baseline (speedup 1.0000x reference)
; __device__ __forceinline__ float sum_x16(float v) { return v + __shfl_xor(v, 16); }
; __device__ __forceinline__ float sum_x32(float v) { return v + __shfl_xor(v, 32); }
; __device__ __forceinline__ unsigned cvt_pk_bf16(float lo, float hi) { unsigned r; asm volatile("v_cvt_pk_bf16_f32 %0, %1, %2" : "=v"(r) : "v"(lo), "v"(hi)); return r; }
;     __device__ __forceinline__ void operator()(const f32x4 (&acc)[2][2][4][2], const Unit& u, int wr, int wc, int fr, int fq) const {
; #pragma unroll
;         for (int ai = 0; ai < 2; ++ai)
; #pragma unroll
;             for (int m = 0; m < 4; ++m) {
;                 const int row = u.pm * BM + ai * HALF + wr * 64 + m * 16 + fr;
;                 float s = 0.f;
; #pragma unroll
;                 for (int bj = 0; bj < 2; ++bj)
; #pragma unroll
;                     for (int n = 0; n < 2; ++n) {
;                         const int col = u.pn * BM + bj * HALF + wc * 32 + n * 16 + fq * 4;
;                         f32x4 h = acc[ai][bj][m][n];
;                         if (mode) { const u32x2 hb = *(const u32x2*)(HB + (size_t)row * DM + col); h[0] += bflo(hb.x); h[1] += bfhi(hb.x); h[2] += bflo(hb.y); h[3] += bfhi(hb.y); }
;                         else h = h + *(const f32x4*)(xp + (size_t)row * DM + col);
;                         u32x2 w; w.x = cvt_pk_bf16(h[0], h[1]); w.y = cvt_pk_bf16(h[2], h[3]);
;                         *(u32x2*)(HB + (size_t)row * DM + col) = w;
;                         s += (h[0] * h[0] + h[1] * h[1]) + (h[2] * h[2] + h[3] * h[3]);
;                     }
;                 s = sum_x32(sum_x16(s));
;                 if (fq == 0) ss[(size_t)row * 16 + u.pn * 4 + wc] = s;
.LBB0_1205:
	v_lshl_add_u32 v142, s51, 8, v144
	v_ashrrev_i32_e32 v143, 31, v142
	v_lshl_or_b32 v140, s12, 8, v146
	v_lshlrev_b64 v[152:153], 11, v[142:143]
	v_ashrrev_i32_e32 v141, 31, v140
	v_lshl_add_u64 v[152:153], s[2:3], 0, v[152:153]
	v_lshl_add_u64 v[152:153], v[140:141], 1, v[152:153]
	s_mov_b32 vcc_lo, 0x8000
	s_mov_b32 vcc_hi, 0
	v_lshl_add_u64 v[192:193], v[152:153], 0, vcc
	s_mov_b32 vcc_lo, 0x10000
	s_mov_b32 vcc_hi, 0
	v_lshl_add_u64 v[194:195], v[152:153], 0, vcc
	s_mov_b32 vcc_lo, 0x18000
	s_mov_b32 vcc_hi, 0
	v_lshl_add_u64 v[196:197], v[152:153], 0, vcc
	global_load_dwordx2 v[160:161], v[152:153], off
	global_load_dwordx2 v[162:163], v[152:153], off offset:32
	global_load_dwordx2 v[164:165], v[152:153], off offset:256
	global_load_dwordx2 v[166:167], v[152:153], off offset:288
	global_load_dwordx2 v[168:169], v[192:193], off
	global_load_dwordx2 v[170:171], v[192:193], off offset:32
	global_load_dwordx2 v[172:173], v[192:193], off offset:256
	global_load_dwordx2 v[174:175], v[192:193], off offset:288
	global_load_dwordx2 v[176:177], v[194:195], off
	global_load_dwordx2 v[178:179], v[194:195], off offset:32
	global_load_dwordx2 v[180:181], v[194:195], off offset:256
	global_load_dwordx2 v[182:183], v[194:195], off offset:288
	global_load_dwordx2 v[184:185], v[196:197], off
	global_load_dwordx2 v[186:187], v[196:197], off offset:32
	global_load_dwordx2 v[188:189], v[196:197], off offset:256
	global_load_dwordx2 v[190:191], v[196:197], off offset:288
	v_and_b32_e32 v158, 64, v150
	v_add_u32_e32 v158, 64, v158
	s_lshl_b32 s22, s12, 2
	s_ashr_i32 s23, s22, 31
	s_waitcnt vmcnt(15)
	v_lshlrev_b32_e32 v151, 16, v160
	v_and_b32_e32 v154, 0xffff0000, v160
	v_lshlrev_b32_e32 v156, 16, v161
	v_and_b32_e32 v155, 0xffff0000, v161
	v_add_f32_e32 v151, v124, v151
	v_add_f32_e32 v154, v125, v154
	v_add_f32_e32 v156, v126, v156
	v_add_f32_e32 v155, v127, v155
	v_cvt_pk_bf16_f32 v124, v151, v154
	v_cvt_pk_bf16_f32 v125, v156, v155
	v_mul_f32_e32 v154, v154, v154
	global_store_dwordx2 v[152:153], v[124:125], off
	v_mul_f32_e32 v155, v155, v155
	v_fmac_f32_e32 v154, v151, v151
	v_fmac_f32_e32 v155, v156, v156
	v_add_f32_e32 v151, v154, v155
	s_waitcnt vmcnt(15)
	v_lshlrev_b32_e32 v124, 16, v162
	v_and_b32_e32 v125, 0xffff0000, v162
	v_lshlrev_b32_e32 v126, 16, v163
	v_and_b32_e32 v127, 0xffff0000, v163
	v_add_f32_e32 v124, v120, v124
	v_add_f32_e32 v125, v121, v125
	v_add_f32_e32 v126, v122, v126
	v_add_f32_e32 v127, v123, v127
	v_cvt_pk_bf16_f32 v120, v124, v125
	v_cvt_pk_bf16_f32 v121, v126, v127
	v_mul_f32_e32 v125, v125, v125
	global_store_dwordx2 v[152:153], v[120:121], off offset:32
	v_mul_f32_e32 v127, v127, v127
	v_fmac_f32_e32 v125, v124, v124
	v_fmac_f32_e32 v127, v126, v126
	v_add_f32_e32 v124, v125, v127
	v_add_f32_e32 v124, v151, v124
	s_waitcnt vmcnt(15)
	v_lshlrev_b32_e32 v120, 16, v164
	v_and_b32_e32 v121, 0xffff0000, v164
	v_lshlrev_b32_e32 v122, 16, v165
	v_and_b32_e32 v123, 0xffff0000, v165
	v_add_f32_e32 v157, v116, v120
	v_add_f32_e32 v117, v117, v121
	v_add_f32_e32 v122, v118, v122
	v_add_f32_e32 v123, v119, v123
	v_cvt_pk_bf16_f32 v118, v157, v117
	v_cvt_pk_bf16_f32 v119, v122, v123
	v_mul_f32_e32 v117, v117, v117
	v_mul_f32_e32 v123, v123, v123
	v_fmac_f32_e32 v117, v157, v157
	v_fmac_f32_e32 v123, v122, v122
	v_add_f32_e32 v117, v117, v123
	v_xor_b32_e32 v116, 16, v150
	v_cmp_lt_i32_e32 vcc, v116, v158
	v_add_f32_e32 v117, v124, v117
	global_store_dwordx2 v[152:153], v[118:119], off offset:256
	v_cndmask_b32_e32 v116, v150, v116, vcc
	v_lshlrev_b32_e32 v116, 2, v116
	s_waitcnt vmcnt(15)
	v_lshlrev_b32_e32 v122, 16, v166
	v_and_b32_e32 v120, 0xffff0000, v166
	v_lshlrev_b32_e32 v123, 16, v167
	v_and_b32_e32 v121, 0xffff0000, v167
	v_add_f32_e32 v120, v113, v120
	v_add_f32_e32 v115, v115, v121
	v_add_f32_e32 v122, v112, v122
	v_add_f32_e32 v123, v114, v123
	v_mul_f32_e32 v112, v120, v120
	v_mul_f32_e32 v113, v115, v115
	v_fmac_f32_e32 v112, v122, v122
	v_fmac_f32_e32 v113, v123, v123
	v_add_f32_e32 v112, v112, v113
	v_add_f32_e32 v112, v117, v112
	ds_bpermute_b32 v113, v116, v112
	v_xor_b32_e32 v114, 32, v150
	v_cmp_lt_i32_e32 vcc, v114, v158
	v_cvt_pk_bf16_f32 v118, v122, v120
	v_cvt_pk_bf16_f32 v119, v123, v115
	s_waitcnt lgkmcnt(0)
	v_add_f32_e32 v112, v112, v113
	global_store_dwordx2 v[152:153], v[118:119], off offset:288
	v_cndmask_b32_e32 v114, v150, v114, vcc
	v_lshlrev_b32_e32 v114, 2, v114
	ds_bpermute_b32 v113, v114, v112
	s_and_saveexec_b64 s[24:25], s[6:7]
	s_cbranch_execz .LBB0_1207
	v_lshlrev_b64 v[118:119], 6, v[142:143]
	v_lshl_add_u64 v[118:119], s[34:35], 0, v[118:119]
	v_lshl_add_u64 v[118:119], s[22:23], 2, v[118:119]
	s_lshl_b32 s12, s40, 2
	v_lshl_add_u64 v[118:119], v[118:119], 0, s[12:13]
	s_waitcnt lgkmcnt(0)
	v_add_f32_e32 v112, v112, v113
	global_store_dword v[118:119], v112, off
; __device__ __forceinline__ float sum_x16(float v) { return v + __shfl_xor(v, 16); }
; __device__ __forceinline__ float sum_x32(float v) { return v + __shfl_xor(v, 32); }
; __device__ __forceinline__ unsigned cvt_pk_bf16(float lo, float hi) { unsigned r; asm volatile("v_cvt_pk_bf16_f32 %0, %1, %2" : "=v"(r) : "v"(lo), "v"(hi)); return r; }
;     __device__ __forceinline__ void operator()(const f32x4 (&acc)[2][2][4][2], const Unit& u, int wr, int wc, int fr, int fq) const {
; #pragma unroll
;         for (int ai = 0; ai < 2; ++ai)
; #pragma unroll
;             for (int m = 0; m < 4; ++m) {
;                 const int row = u.pm * BM + ai * HALF + wr * 64 + m * 16 + fr;
;                 float s = 0.f;
; #pragma unroll
;                 for (int bj = 0; bj < 2; ++bj)
; #pragma unroll
;                     for (int n = 0; n < 2; ++n) {
;                         const int col = u.pn * BM + bj * HALF + wc * 32 + n * 16 + fq * 4;
;                         f32x4 h = acc[ai][bj][m][n];
;                         if (mode) { const u32x2 hb = *(const u32x2*)(HB + (size_t)row * DM + col); h[0] += bflo(hb.x); h[1] += bfhi(hb.x); h[2] += bflo(hb.y); h[3] += bfhi(hb.y); }
;                         else h = h + *(const f32x4*)(xp + (size_t)row * DM + col);
;                         u32x2 w; w.x = cvt_pk_bf16(h[0], h[1]); w.y = cvt_pk_bf16(h[2], h[3]);
;                         *(u32x2*)(HB + (size_t)row * DM + col) = w;
;                         s += (h[0] * h[0] + h[1] * h[1]) + (h[2] * h[2] + h[3] * h[3]);
;                     }
;                 s = sum_x32(sum_x16(s));
;                 if (fq == 0) ss[(size_t)row * 16 + u.pn * 4 + wc] = s;
.LBB0_1207:
	s_or_b64 exec, exec, s[24:25]
	v_or_b32_e32 v112, 16, v142
	s_waitcnt lgkmcnt(0)
	v_ashrrev_i32_e32 v113, 31, v112
	v_lshlrev_b64 v[118:119], 11, v[112:113]
	v_lshl_add_u64 v[118:119], s[2:3], 0, v[118:119]
	v_lshl_add_u64 v[118:119], v[140:141], 1, v[118:119]
	s_waitcnt vmcnt(15)
	v_lshlrev_b32_e32 v115, 16, v168
	v_and_b32_e32 v117, 0xffff0000, v168
	v_lshlrev_b32_e32 v120, 16, v169
	v_and_b32_e32 v121, 0xffff0000, v169
	v_add_f32_e32 v115, v108, v115
	v_add_f32_e32 v117, v109, v117
	v_add_f32_e32 v120, v110, v120
	v_add_f32_e32 v121, v111, v121
	v_cvt_pk_bf16_f32 v108, v115, v117
	v_cvt_pk_bf16_f32 v109, v120, v121
	v_mul_f32_e32 v117, v117, v117
	global_store_dwordx2 v[118:119], v[108:109], off
	v_mul_f32_e32 v121, v121, v121
	v_fmac_f32_e32 v117, v115, v115
	v_fmac_f32_e32 v121, v120, v120
	v_add_f32_e32 v115, v117, v121
	s_waitcnt vmcnt(15)
	v_lshlrev_b32_e32 v108, 16, v170
	v_and_b32_e32 v109, 0xffff0000, v170
	v_lshlrev_b32_e32 v110, 16, v171
	v_and_b32_e32 v111, 0xffff0000, v171
	v_add_f32_e32 v108, v104, v108
	v_add_f32_e32 v109, v105, v109
	v_add_f32_e32 v110, v106, v110
	v_add_f32_e32 v111, v107, v111
	v_cvt_pk_bf16_f32 v104, v108, v109
	v_cvt_pk_bf16_f32 v105, v110, v111
	v_mul_f32_e32 v109, v109, v109
	global_store_dwordx2 v[118:119], v[104:105], off offset:32
	v_mul_f32_e32 v111, v111, v111
	v_fmac_f32_e32 v109, v108, v108
	v_fmac_f32_e32 v111, v110, v110
	v_add_f32_e32 v108, v109, v111
	v_add_f32_e32 v108, v115, v108
	s_waitcnt vmcnt(15)
	v_lshlrev_b32_e32 v104, 16, v172
	v_and_b32_e32 v105, 0xffff0000, v172
	v_lshlrev_b32_e32 v106, 16, v173
	v_and_b32_e32 v107, 0xffff0000, v173
	v_add_f32_e32 v104, v100, v104
	v_add_f32_e32 v105, v101, v105
	v_add_f32_e32 v106, v102, v106
	v_add_f32_e32 v107, v103, v107
	v_cvt_pk_bf16_f32 v100, v104, v105
	v_cvt_pk_bf16_f32 v101, v106, v107
	v_mul_f32_e32 v105, v105, v105
	v_mul_f32_e32 v107, v107, v107
	v_fmac_f32_e32 v105, v104, v104
	v_fmac_f32_e32 v107, v106, v106
	v_add_f32_e32 v104, v105, v107
	v_add_f32_e32 v104, v108, v104
	global_store_dwordx2 v[118:119], v[100:101], off offset:256
	s_waitcnt vmcnt(15)
	v_lshlrev_b32_e32 v105, 16, v174
	v_and_b32_e32 v102, 0xffff0000, v174
	v_lshlrev_b32_e32 v106, 16, v175
	v_and_b32_e32 v103, 0xffff0000, v175
	v_add_f32_e32 v102, v97, v102
	v_add_f32_e32 v99, v99, v103
	v_add_f32_e32 v105, v96, v105
	v_add_f32_e32 v106, v98, v106
	v_mul_f32_e32 v96, v102, v102
	v_mul_f32_e32 v97, v99, v99
	v_fmac_f32_e32 v96, v105, v105
	v_fmac_f32_e32 v97, v106, v106
	v_add_f32_e32 v96, v96, v97
	v_add_f32_e32 v96, v104, v96
	ds_bpermute_b32 v97, v116, v96
	v_cvt_pk_bf16_f32 v98, v105, v102
	v_cvt_pk_bf16_f32 v99, v106, v99
	global_store_dwordx2 v[118:119], v[98:99], off offset:288
	s_waitcnt lgkmcnt(0)
	v_add_f32_e32 v96, v96, v97
	ds_bpermute_b32 v97, v114, v96
	s_and_saveexec_b64 s[24:25], s[6:7]
	s_cbranch_execz .LBB0_1209
	v_lshlrev_b64 v[98:99], 6, v[112:113]
	v_lshl_add_u64 v[98:99], s[34:35], 0, v[98:99]
	v_lshl_add_u64 v[98:99], s[22:23], 2, v[98:99]
	s_lshl_b32 s12, s40, 2
	v_lshl_add_u64 v[98:99], v[98:99], 0, s[12:13]
	s_waitcnt lgkmcnt(0)
	v_add_f32_e32 v96, v96, v97
	global_store_dword v[98:99], v96, off
.LBB0_1209:
	s_or_b64 exec, exec, s[24:25]
	v_or_b32_e32 v96, 32, v142
	s_waitcnt lgkmcnt(0)
	v_ashrrev_i32_e32 v97, 31, v96
	v_lshlrev_b64 v[98:99], 11, v[96:97]
	v_lshl_add_u64 v[98:99], s[2:3], 0, v[98:99]
	v_lshl_add_u64 v[98:99], v[140:141], 1, v[98:99]
	s_waitcnt vmcnt(15)
	v_lshlrev_b32_e32 v102, 16, v176
	v_and_b32_e32 v100, 0xffff0000, v176
	v_lshlrev_b32_e32 v103, 16, v177
	v_and_b32_e32 v101, 0xffff0000, v177
	v_add_f32_e32 v102, v92, v102
	v_add_f32_e32 v100, v93, v100
	v_add_f32_e32 v103, v94, v103
	v_add_f32_e32 v101, v95, v101
	v_cvt_pk_bf16_f32 v92, v102, v100
	v_cvt_pk_bf16_f32 v93, v103, v101
	v_mul_f32_e32 v100, v100, v100
	global_store_dwordx2 v[98:99], v[92:93], off
	v_mul_f32_e32 v101, v101, v101
	v_fmac_f32_e32 v100, v102, v102
	v_fmac_f32_e32 v101, v103, v103
	v_add_f32_e32 v100, v100, v101
	s_waitcnt vmcnt(15)
	v_lshlrev_b32_e32 v92, 16, v178
	v_and_b32_e32 v93, 0xffff0000, v178
	v_lshlrev_b32_e32 v94, 16, v179
	v_and_b32_e32 v95, 0xffff0000, v179
	v_add_f32_e32 v92, v88, v92
	v_add_f32_e32 v93, v89, v93
	v_add_f32_e32 v94, v90, v94
	v_add_f32_e32 v95, v91, v95
	v_cvt_pk_bf16_f32 v88, v92, v93
	v_cvt_pk_bf16_f32 v89, v94, v95
	v_mul_f32_e32 v93, v93, v93
	global_store_dwordx2 v[98:99], v[88:89], off offset:32
	v_mul_f32_e32 v95, v95, v95
	v_fmac_f32_e32 v93, v92, v92
	v_fmac_f32_e32 v95, v94, v94
	v_add_f32_e32 v92, v93, v95
	v_add_f32_e32 v92, v100, v92
	s_waitcnt vmcnt(15)
	v_lshlrev_b32_e32 v88, 16, v180
	v_and_b32_e32 v89, 0xffff0000, v180
	v_lshlrev_b32_e32 v90, 16, v181
	v_and_b32_e32 v91, 0xffff0000, v181
	v_add_f32_e32 v88, v84, v88
	v_add_f32_e32 v89, v85, v89
	v_add_f32_e32 v90, v86, v90
	v_add_f32_e32 v91, v87, v91
	v_cvt_pk_bf16_f32 v84, v88, v89
	v_cvt_pk_bf16_f32 v85, v90, v91
	v_mul_f32_e32 v89, v89, v89
	v_mul_f32_e32 v91, v91, v91
	v_fmac_f32_e32 v89, v88, v88
	v_fmac_f32_e32 v91, v90, v90
	v_add_f32_e32 v88, v89, v91
	v_add_f32_e32 v88, v92, v88
	global_store_dwordx2 v[98:99], v[84:85], off offset:256
	s_waitcnt vmcnt(15)
	v_lshlrev_b32_e32 v89, 16, v182
	v_and_b32_e32 v86, 0xffff0000, v182
	v_lshlrev_b32_e32 v90, 16, v183
	v_and_b32_e32 v87, 0xffff0000, v183
	v_add_f32_e32 v86, v81, v86
	v_add_f32_e32 v83, v83, v87
	v_add_f32_e32 v89, v80, v89
	v_add_f32_e32 v90, v82, v90
	v_mul_f32_e32 v80, v86, v86
	v_mul_f32_e32 v81, v83, v83
	v_fmac_f32_e32 v80, v89, v89
	v_fmac_f32_e32 v81, v90, v90
	v_add_f32_e32 v80, v80, v81
	v_add_f32_e32 v80, v88, v80
	ds_bpermute_b32 v81, v116, v80
	v_cvt_pk_bf16_f32 v82, v89, v86
	v_cvt_pk_bf16_f32 v83, v90, v83
	global_store_dwordx2 v[98:99], v[82:83], off offset:288
	s_waitcnt lgkmcnt(0)
	v_add_f32_e32 v80, v80, v81
	ds_bpermute_b32 v81, v114, v80
	s_and_saveexec_b64 s[24:25], s[6:7]
	s_cbranch_execz .LBB0_1211
	v_lshlrev_b64 v[82:83], 6, v[96:97]
	v_lshl_add_u64 v[82:83], s[34:35], 0, v[82:83]
	v_lshl_add_u64 v[82:83], s[22:23], 2, v[82:83]
	s_lshl_b32 s12, s40, 2
	v_lshl_add_u64 v[82:83], v[82:83], 0, s[12:13]
	s_waitcnt lgkmcnt(0)
	v_add_f32_e32 v80, v80, v81
	global_store_dword v[82:83], v80, off
; __device__ __forceinline__ float sum_x16(float v) { return v + __shfl_xor(v, 16); }
; __device__ __forceinline__ float sum_x32(float v) { return v + __shfl_xor(v, 32); }
; __device__ __forceinline__ unsigned cvt_pk_bf16(float lo, float hi) { unsigned r; asm volatile("v_cvt_pk_bf16_f32 %0, %1, %2" : "=v"(r) : "v"(lo), "v"(hi)); return r; }
;     __device__ __forceinline__ void operator()(const f32x4 (&acc)[2][2][4][2], const Unit& u, int wr, int wc, int fr, int fq) const {
; #pragma unroll
;         for (int ai = 0; ai < 2; ++ai)
; #pragma unroll
;             for (int m = 0; m < 4; ++m) {
;                 const int row = u.pm * BM + ai * HALF + wr * 64 + m * 16 + fr;
;                 float s = 0.f;
; #pragma unroll
;                 for (int bj = 0; bj < 2; ++bj)
; #pragma unroll
;                     for (int n = 0; n < 2; ++n) {
;                         const int col = u.pn * BM + bj * HALF + wc * 32 + n * 16 + fq * 4;
;                         f32x4 h = acc[ai][bj][m][n];
;                         if (mode) { const u32x2 hb = *(const u32x2*)(HB + (size_t)row * DM + col); h[0] += bflo(hb.x); h[1] += bfhi(hb.x); h[2] += bflo(hb.y); h[3] += bfhi(hb.y); }
;                         else h = h + *(const f32x4*)(xp + (size_t)row * DM + col);
;                         u32x2 w; w.x = cvt_pk_bf16(h[0], h[1]); w.y = cvt_pk_bf16(h[2], h[3]);
;                         *(u32x2*)(HB + (size_t)row * DM + col) = w;
;                         s += (h[0] * h[0] + h[1] * h[1]) + (h[2] * h[2] + h[3] * h[3]);
;                     }
;                 s = sum_x32(sum_x16(s));
;                 if (fq == 0) ss[(size_t)row * 16 + u.pn * 4 + wc] = s;
.LBB0_1211:
	s_or_b64 exec, exec, s[24:25]
	v_or_b32_e32 v80, 48, v142
	s_waitcnt lgkmcnt(0)
	v_ashrrev_i32_e32 v81, 31, v80
	v_lshlrev_b64 v[82:83], 11, v[80:81]
	v_lshl_add_u64 v[82:83], s[2:3], 0, v[82:83]
	v_lshl_add_u64 v[82:83], v[140:141], 1, v[82:83]
	s_waitcnt vmcnt(15)
	v_lshlrev_b32_e32 v86, 16, v184
	v_and_b32_e32 v84, 0xffff0000, v184
	v_lshlrev_b32_e32 v87, 16, v185
	v_and_b32_e32 v85, 0xffff0000, v185
	v_add_f32_e32 v86, v76, v86
	v_add_f32_e32 v84, v77, v84
	v_add_f32_e32 v87, v78, v87
	v_add_f32_e32 v85, v79, v85
	v_cvt_pk_bf16_f32 v76, v86, v84
	v_cvt_pk_bf16_f32 v77, v87, v85
	v_mul_f32_e32 v84, v84, v84
	global_store_dwordx2 v[82:83], v[76:77], off
	v_mul_f32_e32 v85, v85, v85
	v_fmac_f32_e32 v84, v86, v86
	v_fmac_f32_e32 v85, v87, v87
	v_add_f32_e32 v84, v84, v85
	s_waitcnt vmcnt(15)
	v_lshlrev_b32_e32 v76, 16, v186
	v_and_b32_e32 v77, 0xffff0000, v186
	v_lshlrev_b32_e32 v78, 16, v187
	v_and_b32_e32 v79, 0xffff0000, v187
	v_add_f32_e32 v76, v72, v76
	v_add_f32_e32 v77, v73, v77
	v_add_f32_e32 v78, v74, v78
	v_add_f32_e32 v79, v75, v79
	v_cvt_pk_bf16_f32 v72, v76, v77
	v_cvt_pk_bf16_f32 v73, v78, v79
	v_mul_f32_e32 v77, v77, v77
	global_store_dwordx2 v[82:83], v[72:73], off offset:32
	v_mul_f32_e32 v79, v79, v79
	v_fmac_f32_e32 v77, v76, v76
	v_fmac_f32_e32 v79, v78, v78
	v_add_f32_e32 v76, v77, v79
	v_add_f32_e32 v76, v84, v76
	s_waitcnt vmcnt(15)
	v_lshlrev_b32_e32 v72, 16, v188
	v_and_b32_e32 v73, 0xffff0000, v188
	v_lshlrev_b32_e32 v74, 16, v189
	v_and_b32_e32 v75, 0xffff0000, v189
	v_add_f32_e32 v72, v68, v72
	v_add_f32_e32 v73, v69, v73
	v_add_f32_e32 v74, v70, v74
	v_add_f32_e32 v75, v71, v75
	v_cvt_pk_bf16_f32 v68, v72, v73
	v_cvt_pk_bf16_f32 v69, v74, v75
	v_mul_f32_e32 v73, v73, v73
	v_mul_f32_e32 v75, v75, v75
	v_fmac_f32_e32 v73, v72, v72
	v_fmac_f32_e32 v75, v74, v74
	v_add_f32_e32 v72, v73, v75
	v_add_f32_e32 v72, v76, v72
	global_store_dwordx2 v[82:83], v[68:69], off offset:256
	s_waitcnt vmcnt(15)
	v_lshlrev_b32_e32 v73, 16, v190
	v_and_b32_e32 v70, 0xffff0000, v190
	v_lshlrev_b32_e32 v74, 16, v191
	v_and_b32_e32 v71, 0xffff0000, v191
	v_add_f32_e32 v70, v65, v70
	v_add_f32_e32 v67, v67, v71
	v_add_f32_e32 v73, v64, v73
	v_add_f32_e32 v74, v66, v74
	v_mul_f32_e32 v64, v70, v70
	v_mul_f32_e32 v65, v67, v67
	v_fmac_f32_e32 v64, v73, v73
	v_fmac_f32_e32 v65, v74, v74
	v_add_f32_e32 v64, v64, v65
	v_add_f32_e32 v64, v72, v64
	ds_bpermute_b32 v65, v116, v64
	v_cvt_pk_bf16_f32 v66, v73, v70
	v_cvt_pk_bf16_f32 v67, v74, v67
	global_store_dwordx2 v[82:83], v[66:67], off offset:288
	s_waitcnt lgkmcnt(0)
	v_add_f32_e32 v64, v64, v65
	ds_bpermute_b32 v65, v114, v64
	s_and_saveexec_b64 s[24:25], s[6:7]
	s_cbranch_execz .LBB0_1213
	v_lshlrev_b64 v[66:67], 6, v[80:81]
	v_lshl_add_u64 v[66:67], s[34:35], 0, v[66:67]
	v_lshl_add_u64 v[66:67], s[22:23], 2, v[66:67]
	s_lshl_b32 s12, s40, 2
	v_lshl_add_u64 v[66:67], v[66:67], 0, s[12:13]
	s_waitcnt lgkmcnt(0)
	v_add_f32_e32 v64, v64, v65
	global_store_dword v[66:67], v64, off
.LBB0_1213:
	s_or_b64 exec, exec, s[24:25]
	v_add_u32_e32 v64, 0x80, v142
	s_waitcnt lgkmcnt(0)
	v_ashrrev_i32_e32 v65, 31, v64
	v_lshlrev_b64 v[66:67], 11, v[64:65]
	v_lshl_add_u64 v[66:67], s[2:3], 0, v[66:67]
	v_lshl_add_u64 v[66:67], v[140:141], 1, v[66:67]
	s_mov_b32 vcc_lo, 0x8000
	s_mov_b32 vcc_hi, 0
	v_lshl_add_u64 v[192:193], v[66:67], 0, vcc
	s_mov_b32 vcc_lo, 0x10000
	s_mov_b32 vcc_hi, 0
	v_lshl_add_u64 v[194:195], v[66:67], 0, vcc
	s_mov_b32 vcc_lo, 0x18000
	s_mov_b32 vcc_hi, 0
	v_lshl_add_u64 v[196:197], v[66:67], 0, vcc
	global_load_dwordx2 v[160:161], v[66:67], off
	global_load_dwordx2 v[162:163], v[66:67], off offset:32
	global_load_dwordx2 v[164:165], v[66:67], off offset:256
	global_load_dwordx2 v[166:167], v[66:67], off offset:288
	global_load_dwordx2 v[168:169], v[192:193], off
	global_load_dwordx2 v[170:171], v[192:193], off offset:32
	global_load_dwordx2 v[172:173], v[192:193], off offset:256
	global_load_dwordx2 v[174:175], v[192:193], off offset:288
	global_load_dwordx2 v[176:177], v[194:195], off
	global_load_dwordx2 v[178:179], v[194:195], off offset:32
	global_load_dwordx2 v[180:181], v[194:195], off offset:256
	global_load_dwordx2 v[182:183], v[194:195], off offset:288
	global_load_dwordx2 v[184:185], v[196:197], off
	global_load_dwordx2 v[186:187], v[196:197], off offset:32
	global_load_dwordx2 v[188:189], v[196:197], off offset:256
	global_load_dwordx2 v[190:191], v[196:197], off offset:288
	s_waitcnt vmcnt(15)
	v_lshlrev_b32_e32 v70, 16, v160
	v_and_b32_e32 v68, 0xffff0000, v160
	v_lshlrev_b32_e32 v71, 16, v161
	v_and_b32_e32 v69, 0xffff0000, v161
	v_add_f32_e32 v70, v60, v70
	v_add_f32_e32 v68, v61, v68
	v_add_f32_e32 v71, v62, v71
	v_add_f32_e32 v69, v63, v69
	v_cvt_pk_bf16_f32 v60, v70, v68
	v_cvt_pk_bf16_f32 v61, v71, v69
	v_mul_f32_e32 v68, v68, v68
	global_store_dwordx2 v[66:67], v[60:61], off
	v_mul_f32_e32 v69, v69, v69
	v_fmac_f32_e32 v68, v70, v70
	v_fmac_f32_e32 v69, v71, v71
	v_add_f32_e32 v68, v68, v69
	s_waitcnt vmcnt(15)
	v_lshlrev_b32_e32 v60, 16, v162
	v_and_b32_e32 v61, 0xffff0000, v162
	v_lshlrev_b32_e32 v62, 16, v163
	v_and_b32_e32 v63, 0xffff0000, v163
	v_add_f32_e32 v60, v56, v60
	v_add_f32_e32 v61, v57, v61
	v_add_f32_e32 v62, v58, v62
	v_add_f32_e32 v63, v59, v63
	v_cvt_pk_bf16_f32 v56, v60, v61
	v_cvt_pk_bf16_f32 v57, v62, v63
	v_mul_f32_e32 v61, v61, v61
	global_store_dwordx2 v[66:67], v[56:57], off offset:32
	v_mul_f32_e32 v63, v63, v63
	v_fmac_f32_e32 v61, v60, v60
	v_fmac_f32_e32 v63, v62, v62
	v_add_f32_e32 v60, v61, v63
	v_add_f32_e32 v60, v68, v60
	s_waitcnt vmcnt(15)
	v_lshlrev_b32_e32 v56, 16, v164
	v_and_b32_e32 v57, 0xffff0000, v164
	v_lshlrev_b32_e32 v58, 16, v165
	v_and_b32_e32 v59, 0xffff0000, v165
	v_add_f32_e32 v56, v52, v56
	v_add_f32_e32 v57, v53, v57
	v_add_f32_e32 v58, v54, v58
	v_add_f32_e32 v59, v55, v59
	v_cvt_pk_bf16_f32 v52, v56, v57
	v_cvt_pk_bf16_f32 v53, v58, v59
	v_mul_f32_e32 v57, v57, v57
	v_mul_f32_e32 v59, v59, v59
	v_fmac_f32_e32 v57, v56, v56
	v_fmac_f32_e32 v59, v58, v58
	v_add_f32_e32 v56, v57, v59
	v_add_f32_e32 v56, v60, v56
	global_store_dwordx2 v[66:67], v[52:53], off offset:256
	s_waitcnt vmcnt(15)
	v_lshlrev_b32_e32 v57, 16, v166
	v_and_b32_e32 v54, 0xffff0000, v166
	v_lshlrev_b32_e32 v58, 16, v167
	v_and_b32_e32 v55, 0xffff0000, v167
	v_add_f32_e32 v54, v49, v54
	v_add_f32_e32 v51, v51, v55
	v_add_f32_e32 v57, v48, v57
	v_add_f32_e32 v58, v50, v58
	v_mul_f32_e32 v48, v54, v54
	v_mul_f32_e32 v49, v51, v51
	v_fmac_f32_e32 v48, v57, v57
	v_fmac_f32_e32 v49, v58, v58
	v_add_f32_e32 v48, v48, v49
	v_add_f32_e32 v48, v56, v48
	ds_bpermute_b32 v49, v116, v48
	v_cvt_pk_bf16_f32 v50, v57, v54
	v_cvt_pk_bf16_f32 v51, v58, v51
	global_store_dwordx2 v[66:67], v[50:51], off offset:288
	s_waitcnt lgkmcnt(0)
	v_add_f32_e32 v48, v48, v49
	ds_bpermute_b32 v49, v114, v48
	s_and_saveexec_b64 s[24:25], s[6:7]
	s_cbranch_execz .LBB0_1215
; __device__ __forceinline__ float sum_x16(float v) { return v + __shfl_xor(v, 16); }
; __device__ __forceinline__ float sum_x32(float v) { return v + __shfl_xor(v, 32); }
; __device__ __forceinline__ unsigned cvt_pk_bf16(float lo, float hi) { unsigned r; asm volatile("v_cvt_pk_bf16_f32 %0, %1, %2" : "=v"(r) : "v"(lo), "v"(hi)); return r; }
;     __device__ __forceinline__ void operator()(const f32x4 (&acc)[2][2][4][2], const Unit& u, int wr, int wc, int fr, int fq) const {
; #pragma unroll
;         for (int ai = 0; ai < 2; ++ai)
; #pragma unroll
;             for (int m = 0; m < 4; ++m) {
;                 const int row = u.pm * BM + ai * HALF + wr * 64 + m * 16 + fr;
;                 float s = 0.f;
; #pragma unroll
;                 for (int bj = 0; bj < 2; ++bj)
; #pragma unroll
;                     for (int n = 0; n < 2; ++n) {
;                         const int col = u.pn * BM + bj * HALF + wc * 32 + n * 16 + fq * 4;
;                         f32x4 h = acc[ai][bj][m][n];
;                         if (mode) { const u32x2 hb = *(const u32x2*)(HB + (size_t)row * DM + col); h[0] += bflo(hb.x); h[1] += bfhi(hb.x); h[2] += bflo(hb.y); h[3] += bfhi(hb.y); }
;                         else h = h + *(const f32x4*)(xp + (size_t)row * DM + col);
;                         u32x2 w; w.x = cvt_pk_bf16(h[0], h[1]); w.y = cvt_pk_bf16(h[2], h[3]);
;                         *(u32x2*)(HB + (size_t)row * DM + col) = w;
;                         s += (h[0] * h[0] + h[1] * h[1]) + (h[2] * h[2] + h[3] * h[3]);
;                     }
;                 s = sum_x32(sum_x16(s));
;                 if (fq == 0) ss[(size_t)row * 16 + u.pn * 4 + wc] = s;
	v_lshlrev_b64 v[50:51], 6, v[64:65]
	v_lshl_add_u64 v[50:51], s[34:35], 0, v[50:51]
	v_lshl_add_u64 v[50:51], s[22:23], 2, v[50:51]
	s_lshl_b32 s12, s40, 2
	v_lshl_add_u64 v[50:51], v[50:51], 0, s[12:13]
	s_waitcnt lgkmcnt(0)
	v_add_f32_e32 v48, v48, v49
	global_store_dword v[50:51], v48, off
.LBB0_1215:
	s_or_b64 exec, exec, s[24:25]
	v_add_u32_e32 v48, 0x90, v142
	s_waitcnt lgkmcnt(0)
	v_ashrrev_i32_e32 v49, 31, v48
	v_lshlrev_b64 v[50:51], 11, v[48:49]
	v_lshl_add_u64 v[50:51], s[2:3], 0, v[50:51]
	v_lshl_add_u64 v[50:51], v[140:141], 1, v[50:51]
	s_waitcnt vmcnt(15)
	v_lshlrev_b32_e32 v54, 16, v168
	v_and_b32_e32 v52, 0xffff0000, v168
	v_lshlrev_b32_e32 v55, 16, v169
	v_and_b32_e32 v53, 0xffff0000, v169
	v_add_f32_e32 v54, v44, v54
	v_add_f32_e32 v52, v45, v52
	v_add_f32_e32 v55, v46, v55
	v_add_f32_e32 v53, v47, v53
	v_cvt_pk_bf16_f32 v44, v54, v52
	v_cvt_pk_bf16_f32 v45, v55, v53
	v_mul_f32_e32 v52, v52, v52
	global_store_dwordx2 v[50:51], v[44:45], off
	v_mul_f32_e32 v53, v53, v53
	v_fmac_f32_e32 v52, v54, v54
	v_fmac_f32_e32 v53, v55, v55
	v_add_f32_e32 v52, v52, v53
	s_waitcnt vmcnt(15)
	v_lshlrev_b32_e32 v44, 16, v170
	v_and_b32_e32 v45, 0xffff0000, v170
	v_lshlrev_b32_e32 v46, 16, v171
	v_and_b32_e32 v47, 0xffff0000, v171
	v_add_f32_e32 v44, v40, v44
	v_add_f32_e32 v45, v41, v45
	v_add_f32_e32 v46, v42, v46
	v_add_f32_e32 v47, v43, v47
	v_cvt_pk_bf16_f32 v40, v44, v45
	v_cvt_pk_bf16_f32 v41, v46, v47
	v_mul_f32_e32 v45, v45, v45
	global_store_dwordx2 v[50:51], v[40:41], off offset:32
	v_mul_f32_e32 v47, v47, v47
	v_fmac_f32_e32 v45, v44, v44
	v_fmac_f32_e32 v47, v46, v46
	v_add_f32_e32 v44, v45, v47
	v_add_f32_e32 v44, v52, v44
	s_waitcnt vmcnt(15)
	v_lshlrev_b32_e32 v40, 16, v172
	v_and_b32_e32 v41, 0xffff0000, v172
	v_lshlrev_b32_e32 v42, 16, v173
	v_and_b32_e32 v43, 0xffff0000, v173
	v_add_f32_e32 v40, v36, v40
	v_add_f32_e32 v41, v37, v41
	v_add_f32_e32 v42, v38, v42
	v_add_f32_e32 v43, v39, v43
	v_cvt_pk_bf16_f32 v36, v40, v41
	v_cvt_pk_bf16_f32 v37, v42, v43
	v_mul_f32_e32 v41, v41, v41
	v_mul_f32_e32 v43, v43, v43
	v_fmac_f32_e32 v41, v40, v40
	v_fmac_f32_e32 v43, v42, v42
	v_add_f32_e32 v40, v41, v43
	v_add_f32_e32 v40, v44, v40
	global_store_dwordx2 v[50:51], v[36:37], off offset:256
	s_waitcnt vmcnt(15)
	v_lshlrev_b32_e32 v41, 16, v174
	v_and_b32_e32 v38, 0xffff0000, v174
	v_lshlrev_b32_e32 v42, 16, v175
	v_and_b32_e32 v39, 0xffff0000, v175
	v_add_f32_e32 v38, v33, v38
	v_add_f32_e32 v35, v35, v39
	v_add_f32_e32 v41, v32, v41
	v_add_f32_e32 v42, v34, v42
	v_mul_f32_e32 v32, v38, v38
	v_mul_f32_e32 v33, v35, v35
	v_fmac_f32_e32 v32, v41, v41
	v_fmac_f32_e32 v33, v42, v42
	v_add_f32_e32 v32, v32, v33
	v_add_f32_e32 v32, v40, v32
	ds_bpermute_b32 v33, v116, v32
	v_cvt_pk_bf16_f32 v34, v41, v38
	v_cvt_pk_bf16_f32 v35, v42, v35
	global_store_dwordx2 v[50:51], v[34:35], off offset:288
	s_waitcnt lgkmcnt(0)
	v_add_f32_e32 v32, v32, v33
	ds_bpermute_b32 v33, v114, v32
	s_and_saveexec_b64 s[24:25], s[6:7]
	s_cbranch_execz .LBB0_1217
	v_lshlrev_b64 v[34:35], 6, v[48:49]
	v_lshl_add_u64 v[34:35], s[34:35], 0, v[34:35]
	v_lshl_add_u64 v[34:35], s[22:23], 2, v[34:35]
	s_lshl_b32 s12, s40, 2
	v_lshl_add_u64 v[34:35], v[34:35], 0, s[12:13]
	s_waitcnt lgkmcnt(0)
	v_add_f32_e32 v32, v32, v33
	global_store_dword v[34:35], v32, off
; __device__ __forceinline__ float sum_x16(float v) { return v + __shfl_xor(v, 16); }
; __device__ __forceinline__ float sum_x32(float v) { return v + __shfl_xor(v, 32); }
; __device__ __forceinline__ unsigned cvt_pk_bf16(float lo, float hi) { unsigned r; asm volatile("v_cvt_pk_bf16_f32 %0, %1, %2" : "=v"(r) : "v"(lo), "v"(hi)); return r; }
;     __device__ __forceinline__ void operator()(const f32x4 (&acc)[2][2][4][2], const Unit& u, int wr, int wc, int fr, int fq) const {
; #pragma unroll
;         for (int ai = 0; ai < 2; ++ai)
; #pragma unroll
;             for (int m = 0; m < 4; ++m) {
;                 const int row = u.pm * BM + ai * HALF + wr * 64 + m * 16 + fr;
;                 float s = 0.f;
; #pragma unroll
;                 for (int bj = 0; bj < 2; ++bj)
; #pragma unroll
;                     for (int n = 0; n < 2; ++n) {
;                         const int col = u.pn * BM + bj * HALF + wc * 32 + n * 16 + fq * 4;
;                         f32x4 h = acc[ai][bj][m][n];
;                         if (mode) { const u32x2 hb = *(const u32x2*)(HB + (size_t)row * DM + col); h[0] += bflo(hb.x); h[1] += bfhi(hb.x); h[2] += bflo(hb.y); h[3] += bfhi(hb.y); }
;                         else h = h + *(const f32x4*)(xp + (size_t)row * DM + col);
;                         u32x2 w; w.x = cvt_pk_bf16(h[0], h[1]); w.y = cvt_pk_bf16(h[2], h[3]);
;                         *(u32x2*)(HB + (size_t)row * DM + col) = w;
;                         s += (h[0] * h[0] + h[1] * h[1]) + (h[2] * h[2] + h[3] * h[3]);
;                     }
;                 s = sum_x32(sum_x16(s));
;                 if (fq == 0) ss[(size_t)row * 16 + u.pn * 4 + wc] = s;
.LBB0_1217:
	s_or_b64 exec, exec, s[24:25]
	v_add_u32_e32 v32, 0xa0, v142
	s_waitcnt lgkmcnt(0)
	v_ashrrev_i32_e32 v33, 31, v32
	v_lshlrev_b64 v[34:35], 11, v[32:33]
	v_lshl_add_u64 v[34:35], s[2:3], 0, v[34:35]
	v_lshl_add_u64 v[34:35], v[140:141], 1, v[34:35]
	s_waitcnt vmcnt(15)
	v_lshlrev_b32_e32 v38, 16, v176
	v_and_b32_e32 v36, 0xffff0000, v176
	v_lshlrev_b32_e32 v39, 16, v177
	v_and_b32_e32 v37, 0xffff0000, v177
	v_add_f32_e32 v38, v28, v38
	v_add_f32_e32 v36, v29, v36
	v_add_f32_e32 v39, v30, v39
	v_add_f32_e32 v37, v31, v37
	v_cvt_pk_bf16_f32 v28, v38, v36
	v_cvt_pk_bf16_f32 v29, v39, v37
	v_mul_f32_e32 v36, v36, v36
	global_store_dwordx2 v[34:35], v[28:29], off
	v_mul_f32_e32 v37, v37, v37
	v_fmac_f32_e32 v36, v38, v38
	v_fmac_f32_e32 v37, v39, v39
	v_add_f32_e32 v36, v36, v37
	s_waitcnt vmcnt(15)
	v_lshlrev_b32_e32 v28, 16, v178
	v_and_b32_e32 v29, 0xffff0000, v178
	v_lshlrev_b32_e32 v30, 16, v179
	v_and_b32_e32 v31, 0xffff0000, v179
	v_add_f32_e32 v28, v24, v28
	v_add_f32_e32 v29, v25, v29
	v_add_f32_e32 v30, v26, v30
	v_add_f32_e32 v31, v27, v31
	v_cvt_pk_bf16_f32 v24, v28, v29
	v_cvt_pk_bf16_f32 v25, v30, v31
	v_mul_f32_e32 v29, v29, v29
	global_store_dwordx2 v[34:35], v[24:25], off offset:32
	v_mul_f32_e32 v31, v31, v31
	v_fmac_f32_e32 v29, v28, v28
	v_fmac_f32_e32 v31, v30, v30
	v_add_f32_e32 v28, v29, v31
	v_add_f32_e32 v28, v36, v28
	s_waitcnt vmcnt(15)
	v_lshlrev_b32_e32 v24, 16, v180
	v_and_b32_e32 v25, 0xffff0000, v180
	v_lshlrev_b32_e32 v26, 16, v181
	v_and_b32_e32 v27, 0xffff0000, v181
	v_add_f32_e32 v24, v20, v24
	v_add_f32_e32 v25, v21, v25
	v_add_f32_e32 v26, v22, v26
	v_add_f32_e32 v27, v23, v27
	v_cvt_pk_bf16_f32 v20, v24, v25
	v_cvt_pk_bf16_f32 v21, v26, v27
	v_mul_f32_e32 v25, v25, v25
	v_mul_f32_e32 v27, v27, v27
	v_fmac_f32_e32 v25, v24, v24
	v_fmac_f32_e32 v27, v26, v26
	v_add_f32_e32 v24, v25, v27
	v_add_f32_e32 v24, v28, v24
	global_store_dwordx2 v[34:35], v[20:21], off offset:256
	s_waitcnt vmcnt(15)
	v_lshlrev_b32_e32 v25, 16, v182
	v_and_b32_e32 v22, 0xffff0000, v182
	v_lshlrev_b32_e32 v26, 16, v183
	v_and_b32_e32 v23, 0xffff0000, v183
	v_add_f32_e32 v22, v17, v22
	v_add_f32_e32 v19, v19, v23
	v_add_f32_e32 v25, v16, v25
	v_add_f32_e32 v26, v18, v26
	v_mul_f32_e32 v16, v22, v22
	v_mul_f32_e32 v17, v19, v19
	v_fmac_f32_e32 v16, v25, v25
	v_fmac_f32_e32 v17, v26, v26
	v_add_f32_e32 v16, v16, v17
	v_add_f32_e32 v16, v24, v16
	ds_bpermute_b32 v17, v116, v16
	v_cvt_pk_bf16_f32 v18, v25, v22
	v_cvt_pk_bf16_f32 v19, v26, v19
	global_store_dwordx2 v[34:35], v[18:19], off offset:288
	s_waitcnt lgkmcnt(0)
	v_add_f32_e32 v16, v16, v17
	ds_bpermute_b32 v17, v114, v16
	s_and_saveexec_b64 s[24:25], s[6:7]
	s_cbranch_execz .LBB0_1219
	v_lshlrev_b64 v[18:19], 6, v[32:33]
	v_lshl_add_u64 v[18:19], s[34:35], 0, v[18:19]
	v_lshl_add_u64 v[18:19], s[22:23], 2, v[18:19]
	s_lshl_b32 s12, s40, 2
	v_lshl_add_u64 v[18:19], v[18:19], 0, s[12:13]
	s_waitcnt lgkmcnt(0)
	v_add_f32_e32 v16, v16, v17
	global_store_dword v[18:19], v16, off
.LBB0_1219:
	s_or_b64 exec, exec, s[24:25]
	v_add_u32_e32 v16, 0xb0, v142
	s_waitcnt lgkmcnt(0)
	v_ashrrev_i32_e32 v17, 31, v16
	v_lshlrev_b64 v[18:19], 11, v[16:17]
	v_lshl_add_u64 v[18:19], s[2:3], 0, v[18:19]
	v_lshl_add_u64 v[18:19], v[140:141], 1, v[18:19]
	s_waitcnt vmcnt(15)
	v_lshlrev_b32_e32 v22, 16, v184
	v_and_b32_e32 v20, 0xffff0000, v184
	v_lshlrev_b32_e32 v23, 16, v185
	v_and_b32_e32 v21, 0xffff0000, v185
	v_add_f32_e32 v22, v12, v22
	v_add_f32_e32 v20, v13, v20
	v_add_f32_e32 v23, v14, v23
	v_add_f32_e32 v21, v15, v21
	v_cvt_pk_bf16_f32 v12, v22, v20
	v_cvt_pk_bf16_f32 v13, v23, v21
	v_mul_f32_e32 v20, v20, v20
	global_store_dwordx2 v[18:19], v[12:13], off
	v_mul_f32_e32 v21, v21, v21
	v_fmac_f32_e32 v20, v22, v22
	v_fmac_f32_e32 v21, v23, v23
	v_add_f32_e32 v20, v20, v21
	s_waitcnt vmcnt(15)
	v_lshlrev_b32_e32 v12, 16, v186
	v_and_b32_e32 v13, 0xffff0000, v186
	v_lshlrev_b32_e32 v14, 16, v187
	v_and_b32_e32 v15, 0xffff0000, v187
	v_add_f32_e32 v12, v8, v12
	v_add_f32_e32 v13, v9, v13
	v_add_f32_e32 v14, v10, v14
	v_add_f32_e32 v15, v11, v15
	v_cvt_pk_bf16_f32 v8, v12, v13
	v_cvt_pk_bf16_f32 v9, v14, v15
	v_mul_f32_e32 v13, v13, v13
	global_store_dwordx2 v[18:19], v[8:9], off offset:32
	v_mul_f32_e32 v15, v15, v15
	v_fmac_f32_e32 v13, v12, v12
	v_fmac_f32_e32 v15, v14, v14
	v_add_f32_e32 v12, v13, v15
	v_add_f32_e32 v12, v20, v12
	s_waitcnt vmcnt(15)
	v_lshlrev_b32_e32 v8, 16, v188
	v_and_b32_e32 v9, 0xffff0000, v188
	v_lshlrev_b32_e32 v10, 16, v189
	v_and_b32_e32 v11, 0xffff0000, v189
	v_add_f32_e32 v8, v4, v8
	v_add_f32_e32 v9, v5, v9
	v_add_f32_e32 v10, v6, v10
	v_add_f32_e32 v11, v7, v11
	v_cvt_pk_bf16_f32 v4, v8, v9
	v_cvt_pk_bf16_f32 v5, v10, v11
	v_mul_f32_e32 v9, v9, v9
	v_mul_f32_e32 v11, v11, v11
	v_fmac_f32_e32 v9, v8, v8
	v_fmac_f32_e32 v11, v10, v10
	v_add_f32_e32 v8, v9, v11
	v_add_f32_e32 v8, v12, v8
	global_store_dwordx2 v[18:19], v[4:5], off offset:256
	s_waitcnt vmcnt(15)
	v_lshlrev_b32_e32 v9, 16, v190
	v_and_b32_e32 v6, 0xffff0000, v190
	v_lshlrev_b32_e32 v10, 16, v191
	v_and_b32_e32 v7, 0xffff0000, v191
	v_add_f32_e32 v6, v1, v6
	v_add_f32_e32 v3, v3, v7
	v_add_f32_e32 v9, v0, v9
	v_add_f32_e32 v10, v2, v10
	v_mul_f32_e32 v0, v6, v6
	v_mul_f32_e32 v1, v3, v3
	v_fmac_f32_e32 v0, v9, v9
	v_fmac_f32_e32 v1, v10, v10
	v_add_f32_e32 v0, v0, v1
	v_add_f32_e32 v0, v8, v0
	ds_bpermute_b32 v1, v116, v0
	v_cvt_pk_bf16_f32 v2, v9, v6
	v_cvt_pk_bf16_f32 v3, v10, v3
	global_store_dwordx2 v[18:19], v[2:3], off offset:288
	s_waitcnt lgkmcnt(0)
	v_add_f32_e32 v0, v0, v1
	ds_bpermute_b32 v1, v114, v0
	s_and_saveexec_b64 s[24:25], s[6:7]
	s_cbranch_execz .LBB0_1221
	v_lshlrev_b64 v[2:3], 6, v[16:17]
	v_lshl_add_u64 v[2:3], s[34:35], 0, v[2:3]
	v_lshl_add_u64 v[2:3], s[22:23], 2, v[2:3]
	s_lshl_b32 s12, s40, 2
	v_lshl_add_u64 v[2:3], v[2:3], 0, s[12:13]
	s_waitcnt lgkmcnt(0)
	v_add_f32_e32 v0, v0, v1
	global_store_dword v[2:3], v0, off
